# phase-2 T=(I+M)^-1: forward substitution on all 4 waves (16 columns each) with v_mfma_f32_16x16x4_f32 for the solved-rows contribution, f32 throughout (was wave-0-only VALU)
# speedup vs baseline: 1.0362x; 1.0157x over previous
; __device__ __forceinline__ u16 f2bf(float f) { return (u16)(cvtpk(f, 0.f) & 0xffffu); }
; __device__ __forceinline__ f32x16 mfma32(bf16x8 a, bf16x8 b, f32x16 c) { return __builtin_amdgcn_mfma_f32_32x32x16_bf16(a, b, c, 0, 0, 0); }
; template <bool SIGNAL>
; __device__ __forceinline__ void phase2(const Params& p, unsigned char* smem, const int lo, const int hi, const int worker, const int nworkers) {
;     ...
;     const int ti = wave >> 1, tj = wave & 1;
;     f32x16 kk, qk;
; #pragma unroll
;     for (int r = 0; r < 16; ++r) { kk[r] = 0.f; qk[r] = 0.f; }
; #pragma unroll
;     for (int s = 0; s < 8; ++s) {
;       bf16x8 bj = *(const bf16x8*)(sk + (32 * tj + l31) * 136 + s * 16 + hf * 8);
;       bf16x8 ak = *(const bf16x8*)(sk + (32 * ti + l31) * 136 + s * 16 + hf * 8);
;       bf16x8 aq = *(const bf16x8*)(sq + (32 * ti + l31) * 136 + s * 16 + hf * 8);
;       kk = mfma32(ak, bj, kk); qk = mfma32(aq, bj, qk);
;     }
;     __syncthreads();
;     u16* Tg = TA + (size_t)it * 8704; u16* Ag = Tg + 4096; float* SCg = (float*)(Tg + 8192);
;     {
;       const int j = 32 * tj + l31; const float gcj = sgc[j];
; #pragma unroll
;       for (int r = 0; r < 16; ++r) {
;         const int i = 32 * ti + 8 * (r >> 2) + 4 * hf + (r & 3);
;         const float gci = sgc[i]; const float bi = sbeta[i];
;         const float dec = __expf(gci - gcj);
;         sM[i * 68 + j] = (j < i) ? bi * kk[r] * dec : 0.f;
;         Ag[i * 64 + j] = f2bf((j <= i) ? qk[r] * dec : 0.f);
;       }
;     }
.LBB0_298:
	ds_read_b128 v[0:3], v109 offset:51712
	ds_read_b128 v[4:7], v108 offset:51712
	ds_read_b128 v[166:169], v108 offset:51744
	s_mul_hi_i32 s36, s91, 0x4400
	s_mulk_i32 s91, 0x4400
	v_readlane_b32 s37, v247, 7
	s_waitcnt lgkmcnt(1)
	v_mfma_f32_32x32x16_bf16 v[16:31], v[0:3], v[4:7], 0
	ds_read_b128 v[0:3], v109 offset:34304
	ds_read_b128 v[170:173], v109 offset:34336
	ds_read_b128 v[174:177], v109 offset:51744
	s_add_u32 s38, s37, s91
	v_readlane_b32 s37, v247, 8
	s_addc_u32 s39, s37, s36
	s_add_u32 s42, s38, 0x2000
	v_readlane_b32 s36, v247, 45
	s_waitcnt lgkmcnt(2)
	v_mfma_f32_32x32x16_bf16 v[0:15], v[0:3], v[4:7], 0
	s_addc_u32 s43, s39, 0
	v_readlane_b32 s37, v247, 46
	s_waitcnt lgkmcnt(0)
	v_mfma_f32_32x32x16_bf16 v[16:31], v[174:177], v[166:169], v[16:31]
	v_mfma_f32_32x32x16_bf16 v[0:15], v[170:173], v[166:169], v[0:15]
	ds_read_b128 v[166:169], v108 offset:51776
	ds_read_b128 v[170:173], v109 offset:51776
	ds_read_b128 v[174:177], v109 offset:34368
	s_waitcnt lgkmcnt(1)
	v_mfma_f32_32x32x16_bf16 v[16:31], v[170:173], v[166:169], v[16:31]
	s_waitcnt lgkmcnt(0)
	v_mfma_f32_32x32x16_bf16 v[0:15], v[174:177], v[166:169], v[0:15]
	ds_read_b128 v[166:169], v108 offset:51808
	ds_read_b128 v[170:173], v109 offset:51808
	ds_read_b128 v[174:177], v109 offset:34400
	s_waitcnt lgkmcnt(1)
	v_mfma_f32_32x32x16_bf16 v[16:31], v[170:173], v[166:169], v[16:31]
	s_waitcnt lgkmcnt(0)
	v_mfma_f32_32x32x16_bf16 v[0:15], v[174:177], v[166:169], v[0:15]
	ds_read_b128 v[166:169], v108 offset:51840
	ds_read_b128 v[170:173], v109 offset:51840
	ds_read_b128 v[174:177], v109 offset:34432
	s_waitcnt lgkmcnt(1)
	v_mfma_f32_32x32x16_bf16 v[16:31], v[170:173], v[166:169], v[16:31]
	s_waitcnt lgkmcnt(0)
	v_mfma_f32_32x32x16_bf16 v[0:15], v[174:177], v[166:169], v[0:15]
	ds_read_b128 v[166:169], v108 offset:51872
	ds_read_b128 v[170:173], v109 offset:51872
	ds_read_b128 v[174:177], v109 offset:34464
	s_waitcnt lgkmcnt(1)
	v_mfma_f32_32x32x16_bf16 v[16:31], v[170:173], v[166:169], v[16:31]
	s_waitcnt lgkmcnt(0)
	v_mfma_f32_32x32x16_bf16 v[0:15], v[174:177], v[166:169], v[0:15]
	ds_read_b128 v[166:169], v108 offset:51904
	ds_read_b128 v[170:173], v109 offset:51904
	ds_read_b128 v[174:177], v109 offset:34496
	s_waitcnt lgkmcnt(1)
	v_mfma_f32_32x32x16_bf16 v[16:31], v[170:173], v[166:169], v[16:31]
	s_waitcnt lgkmcnt(0)
	v_mfma_f32_32x32x16_bf16 v[0:15], v[174:177], v[166:169], v[0:15]
	ds_read_b128 v[166:169], v108 offset:51936
	ds_read_b128 v[170:173], v109 offset:51936
	ds_read_b128 v[174:177], v109 offset:34528
	s_waitcnt lgkmcnt(0)
	s_barrier
	v_mfma_f32_32x32x16_bf16 v[16:31], v[170:173], v[166:169], v[16:31]
	v_mfma_f32_32x32x16_bf16 v[0:15], v[174:177], v[166:169], v[0:15]
	ds_read_b32 v166, v110
	ds_read_b32 v167, v123
	ds_read_b32 v168, v124
	s_waitcnt lgkmcnt(1)
	v_sub_f32_e32 v167, v167, v166
	v_mul_f32_e32 v167, 0x3fb8aa3b, v167
	v_exp_f32_e32 v167, v167
	s_waitcnt lgkmcnt(0)
	s_nop 2
	v_mul_f32_e32 v16, v16, v168
	v_lshl_add_u64 v[168:169], v[70:71], 1, s[42:43]
	v_mul_f32_e32 v0, v0, v167
	v_mul_f32_e32 v16, v16, v167
	v_cvt_pk_bf16_f32 v0, v0, s0
	v_cndmask_b32_e64 v16, 0, v16, s[36:37]
	v_cndmask_b32_e64 v0, v0, 0, s[66:67]
	ds_write_b32 v162, v16
	global_store_short v[168:169], v0, off
	ds_read_b32 v0, v125
	ds_read_b32 v16, v126
	v_readlane_b32 s36, v247, 47
	v_readlane_b32 s37, v247, 48
	s_waitcnt lgkmcnt(1)
	v_sub_f32_e32 v0, v0, v166
	v_mul_f32_e32 v0, 0x3fb8aa3b, v0
	v_exp_f32_e32 v0, v0
	s_waitcnt lgkmcnt(0)
	v_mul_f32_e32 v16, v17, v16
	v_mul_f32_e32 v16, v16, v0
	v_mul_f32_e32 v0, v1, v0
	v_cndmask_b32_e64 v16, v16, 0, s[66:67]
	v_cvt_pk_bf16_f32 v0, v0, s0
	ds_write_b32 v162, v16 offset:272
	v_cndmask_b32_e64 v16, v0, 0, s[36:37]
	v_lshl_add_u64 v[0:1], v[72:73], 1, s[42:43]
	global_store_short v[0:1], v16, off
	ds_read_b32 v0, v127
	ds_read_b32 v1, v128
	v_readlane_b32 s36, v247, 49
	v_readlane_b32 s37, v247, 50
	s_waitcnt lgkmcnt(1)
	v_sub_f32_e32 v0, v0, v166
	v_mul_f32_e32 v0, 0x3fb8aa3b, v0
	v_exp_f32_e32 v0, v0
	s_waitcnt lgkmcnt(0)
	v_mul_f32_e32 v1, v18, v1
	v_mul_f32_e32 v1, v1, v0
	v_cndmask_b32_e64 v1, 0, v1, s[36:37]
	v_mul_f32_e32 v0, v2, v0
	v_readlane_b32 s36, v247, 51
	v_cvt_pk_bf16_f32 v0, v0, s0
	v_readlane_b32 s37, v247, 52
	ds_write_b32 v162, v1 offset:544
	s_nop 0
	v_cndmask_b32_e64 v2, v0, 0, s[36:37]
	v_lshl_add_u64 v[0:1], v[74:75], 1, s[42:43]
	global_store_short v[0:1], v2, off
	ds_read_b32 v0, v129
	ds_read_b32 v1, v130
	v_readlane_b32 s36, v247, 53
	v_readlane_b32 s37, v247, 54
	s_waitcnt lgkmcnt(1)
	v_sub_f32_e32 v0, v0, v166
	v_mul_f32_e32 v0, 0x3fb8aa3b, v0
	v_exp_f32_e32 v0, v0
	s_waitcnt lgkmcnt(0)
	v_mul_f32_e32 v1, v19, v1
	v_mul_f32_e32 v1, v1, v0
	v_cndmask_b32_e64 v1, 0, v1, s[36:37]
	v_mul_f32_e32 v0, v3, v0
	v_readlane_b32 s36, v247, 55
	v_cvt_pk_bf16_f32 v0, v0, s0
	v_readlane_b32 s37, v247, 56
	ds_write_b32 v162, v1 offset:816
	s_nop 0
	v_cndmask_b32_e64 v2, v0, 0, s[36:37]
	v_lshl_add_u64 v[0:1], v[76:77], 1, s[42:43]
	global_store_short v[0:1], v2, off
	ds_read_b32 v0, v131
	ds_read_b32 v1, v132
	v_readlane_b32 s36, v247, 57
	v_readlane_b32 s37, v247, 58
	s_waitcnt lgkmcnt(1)
	v_sub_f32_e32 v0, v0, v166
	v_mul_f32_e32 v0, 0x3fb8aa3b, v0
	v_exp_f32_e32 v0, v0
	s_waitcnt lgkmcnt(0)
	v_mul_f32_e32 v1, v20, v1
	v_mul_f32_e32 v1, v1, v0
	v_cndmask_b32_e64 v1, 0, v1, s[36:37]
	v_mul_f32_e32 v0, v4, v0
	v_readlane_b32 s36, v246, 1
	v_cvt_pk_bf16_f32 v0, v0, s0
	v_readlane_b32 s37, v246, 2
	ds_write_b32 v162, v1 offset:2176
	s_nop 0
	v_cndmask_b32_e64 v2, v0, 0, s[36:37]
	v_lshl_add_u64 v[0:1], v[78:79], 1, s[42:43]
	global_store_short v[0:1], v2, off
	ds_read_b32 v0, v133
	ds_read_b32 v1, v134
	v_readlane_b32 s36, v246, 3
	v_readlane_b32 s37, v246, 4
	s_waitcnt lgkmcnt(1)
; __device__ __forceinline__ u16 f2bf(float f) { return (u16)(cvtpk(f, 0.f) & 0xffffu); }
; template <bool SIGNAL>
; __device__ __forceinline__ void phase2(const Params& p, unsigned char* smem, const int lo, const int hi, const int worker, const int nworkers) {
;     ...
;       const int j = 32 * tj + l31; const float gcj = sgc[j];
; #pragma unroll
;       for (int r = 0; r < 16; ++r) {
;         const int i = 32 * ti + 8 * (r >> 2) + 4 * hf + (r & 3);
;         const float gci = sgc[i]; const float bi = sbeta[i];
;         const float dec = __expf(gci - gcj);
;         sM[i * 68 + j] = (j < i) ? bi * kk[r] * dec : 0.f;
;         Ag[i * 64 + j] = f2bf((j <= i) ? qk[r] * dec : 0.f);
;       }
;     }
;     __syncthreads();
	v_sub_f32_e32 v0, v0, v166
	v_mul_f32_e32 v0, 0x3fb8aa3b, v0
	v_exp_f32_e32 v0, v0
	s_waitcnt lgkmcnt(0)
	v_mul_f32_e32 v1, v21, v1
	v_mul_f32_e32 v1, v1, v0
	v_cndmask_b32_e64 v1, 0, v1, s[36:37]
	v_mul_f32_e32 v0, v5, v0
	v_readlane_b32 s36, v246, 5
	v_cvt_pk_bf16_f32 v0, v0, s0
	v_readlane_b32 s37, v246, 6
	ds_write_b32 v162, v1 offset:2448
	s_nop 0
	v_cndmask_b32_e64 v2, v0, 0, s[36:37]
	v_lshl_add_u64 v[0:1], v[80:81], 1, s[42:43]
	global_store_short v[0:1], v2, off
	ds_read_b32 v0, v135
	ds_read_b32 v1, v136
	v_readlane_b32 s36, v246, 7
	v_readlane_b32 s37, v246, 8
	s_waitcnt lgkmcnt(1)
	v_sub_f32_e32 v0, v0, v166
	v_mul_f32_e32 v0, 0x3fb8aa3b, v0
	v_exp_f32_e32 v0, v0
	s_waitcnt lgkmcnt(0)
	v_mul_f32_e32 v1, v22, v1
	v_mul_f32_e32 v1, v1, v0
	v_cndmask_b32_e64 v1, 0, v1, s[36:37]
	v_mul_f32_e32 v0, v6, v0
	v_readlane_b32 s36, v246, 9
	v_cvt_pk_bf16_f32 v0, v0, s0
	v_readlane_b32 s37, v246, 10
	ds_write_b32 v162, v1 offset:2720
	s_nop 0
	v_cndmask_b32_e64 v2, v0, 0, s[36:37]
	v_lshl_add_u64 v[0:1], v[82:83], 1, s[42:43]
	global_store_short v[0:1], v2, off
	ds_read_b32 v0, v137
	ds_read_b32 v1, v138
	v_readlane_b32 s36, v246, 11
	v_readlane_b32 s37, v246, 12
	s_waitcnt lgkmcnt(1)
	v_sub_f32_e32 v0, v0, v166
	v_mul_f32_e32 v0, 0x3fb8aa3b, v0
	v_exp_f32_e32 v0, v0
	s_waitcnt lgkmcnt(0)
	v_mul_f32_e32 v1, v23, v1
	v_mul_f32_e32 v1, v1, v0
	v_cndmask_b32_e64 v1, 0, v1, s[36:37]
	v_mul_f32_e32 v0, v7, v0
	v_readlane_b32 s36, v246, 13
	v_cvt_pk_bf16_f32 v0, v0, s0
	v_readlane_b32 s37, v246, 14
	ds_write_b32 v162, v1 offset:2992
	s_nop 0
	v_cndmask_b32_e64 v2, v0, 0, s[36:37]
	v_lshl_add_u64 v[0:1], v[84:85], 1, s[42:43]
	global_store_short v[0:1], v2, off
	ds_read_b32 v0, v139
	ds_read_b32 v1, v140
	v_readlane_b32 s36, v246, 15
	v_readlane_b32 s37, v246, 16
	s_waitcnt lgkmcnt(1)
	v_sub_f32_e32 v0, v0, v166
	v_mul_f32_e32 v0, 0x3fb8aa3b, v0
	v_exp_f32_e32 v0, v0
	s_waitcnt lgkmcnt(0)
	v_mul_f32_e32 v1, v24, v1
	v_mul_f32_e32 v1, v1, v0
	v_cndmask_b32_e64 v1, 0, v1, s[36:37]
	v_mul_f32_e32 v0, v8, v0
	v_readlane_b32 s36, v246, 17
	v_cvt_pk_bf16_f32 v0, v0, s0
	v_readlane_b32 s37, v246, 18
	ds_write_b32 v162, v1 offset:4352
	s_nop 0
	v_cndmask_b32_e64 v2, v0, 0, s[36:37]
	v_lshl_add_u64 v[0:1], v[86:87], 1, s[42:43]
	global_store_short v[0:1], v2, off
	ds_read_b32 v0, v141
	ds_read_b32 v1, v142
	v_readlane_b32 s36, v246, 19
	v_readlane_b32 s37, v246, 20
	s_waitcnt lgkmcnt(1)
	v_sub_f32_e32 v0, v0, v166
	v_mul_f32_e32 v0, 0x3fb8aa3b, v0
	v_exp_f32_e32 v0, v0
	s_waitcnt lgkmcnt(0)
	v_mul_f32_e32 v1, v25, v1
	v_mul_f32_e32 v1, v1, v0
	v_cndmask_b32_e64 v1, 0, v1, s[36:37]
	v_mul_f32_e32 v0, v9, v0
	v_readlane_b32 s36, v246, 21
	v_cvt_pk_bf16_f32 v0, v0, s0
	v_readlane_b32 s37, v246, 22
	ds_write_b32 v162, v1 offset:4624
	s_nop 0
	v_cndmask_b32_e64 v2, v0, 0, s[36:37]
	v_lshl_add_u64 v[0:1], v[88:89], 1, s[42:43]
	global_store_short v[0:1], v2, off
	ds_read_b32 v0, v143
	ds_read_b32 v1, v144
	s_waitcnt lgkmcnt(1)
	v_sub_f32_e32 v0, v0, v166
	v_mul_f32_e32 v0, 0x3fb8aa3b, v0
	v_exp_f32_e32 v0, v0
	s_waitcnt lgkmcnt(0)
	v_mul_f32_e32 v1, v26, v1
	v_mul_f32_e32 v1, v1, v0
	v_mul_f32_e32 v0, v10, v0
	v_cndmask_b32_e64 v1, 0, v1, s[10:11]
	v_cvt_pk_bf16_f32 v0, v0, s0
	ds_write_b32 v162, v1 offset:4896
	v_cndmask_b32_e64 v2, v0, 0, s[12:13]
	v_lshl_add_u64 v[0:1], v[90:91], 1, s[42:43]
	global_store_short v[0:1], v2, off
	ds_read_b32 v0, v145
	ds_read_b32 v1, v146
	s_waitcnt lgkmcnt(1)
	v_sub_f32_e32 v0, v0, v166
	v_mul_f32_e32 v0, 0x3fb8aa3b, v0
	v_exp_f32_e32 v0, v0
	s_waitcnt lgkmcnt(0)
	v_mul_f32_e32 v1, v27, v1
	v_mul_f32_e32 v1, v1, v0
	v_mul_f32_e32 v0, v11, v0
	v_cndmask_b32_e64 v1, 0, v1, s[14:15]
	v_cvt_pk_bf16_f32 v0, v0, s0
	ds_write_b32 v162, v1 offset:5168
	v_cndmask_b32_e64 v2, v0, 0, s[16:17]
	v_lshl_add_u64 v[0:1], v[92:93], 1, s[42:43]
	global_store_short v[0:1], v2, off
	ds_read_b32 v0, v147
	ds_read_b32 v1, v148
	s_waitcnt lgkmcnt(1)
	v_sub_f32_e32 v0, v0, v166
	v_mul_f32_e32 v0, 0x3fb8aa3b, v0
	v_exp_f32_e32 v0, v0
	s_waitcnt lgkmcnt(0)
	v_mul_f32_e32 v1, v28, v1
	v_mul_f32_e32 v1, v1, v0
	v_mul_f32_e32 v0, v12, v0
	v_cndmask_b32_e64 v1, 0, v1, s[18:19]
	v_cvt_pk_bf16_f32 v0, v0, s0
	ds_write_b32 v162, v1 offset:6528
	v_cndmask_b32_e64 v2, v0, 0, s[20:21]
	v_lshl_add_u64 v[0:1], v[94:95], 1, s[42:43]
	global_store_short v[0:1], v2, off
	ds_read_b32 v0, v149
	ds_read_b32 v1, v150
	s_waitcnt lgkmcnt(1)
	v_sub_f32_e32 v0, v0, v166
	v_mul_f32_e32 v0, 0x3fb8aa3b, v0
	v_exp_f32_e32 v0, v0
	s_waitcnt lgkmcnt(0)
	v_mul_f32_e32 v1, v29, v1
	v_mul_f32_e32 v1, v1, v0
	v_mul_f32_e32 v0, v13, v0
	v_cndmask_b32_e64 v1, 0, v1, s[6:7]
	v_cvt_pk_bf16_f32 v0, v0, s0
	ds_write_b32 v162, v1 offset:6800
	v_cndmask_b32_e64 v2, v0, 0, s[8:9]
	v_lshl_add_u64 v[0:1], v[96:97], 1, s[42:43]
	global_store_short v[0:1], v2, off
	ds_read_b32 v0, v151
	ds_read_b32 v1, v152
	s_waitcnt lgkmcnt(1)
	v_sub_f32_e32 v0, v0, v166
	v_mul_f32_e32 v0, 0x3fb8aa3b, v0
	v_exp_f32_e32 v0, v0
	s_waitcnt lgkmcnt(0)
	v_mul_f32_e32 v1, v30, v1
	v_mul_f32_e32 v1, v1, v0
	v_mul_f32_e32 v0, v14, v0
	v_cndmask_b32_e64 v1, 0, v1, s[22:23]
	v_cvt_pk_bf16_f32 v0, v0, s0
	ds_write_b32 v162, v1 offset:7072
	v_cndmask_b32_e64 v2, v0, 0, s[24:25]
	v_lshl_add_u64 v[0:1], v[98:99], 1, s[42:43]
	global_store_short v[0:1], v2, off
	ds_read_b32 v0, v153
	ds_read_b32 v1, v154
	s_waitcnt lgkmcnt(1)
	v_sub_f32_e32 v0, v0, v166
	v_mul_f32_e32 v0, 0x3fb8aa3b, v0
	v_exp_f32_e32 v0, v0
	s_waitcnt lgkmcnt(0)
	v_mul_f32_e32 v1, v31, v1
	v_mul_f32_e32 v1, v1, v0
	v_mul_f32_e32 v0, v15, v0
	v_cndmask_b32_e64 v1, 0, v1, s[28:29]
	v_cvt_pk_bf16_f32 v0, v0, s0
	ds_write_b32 v162, v1 offset:7344
	v_cndmask_b32_e64 v2, v0, 0, s[30:31]
	v_lshl_add_u64 v[0:1], v[100:101], 1, s[42:43]
	global_store_short v[0:1], v2, off
	s_waitcnt lgkmcnt(0)
	s_barrier
; template <bool SIGNAL>
; __device__ __forceinline__ void phase2(const Params& p, unsigned char* smem, const int lo, const int hi, const int worker, const int nworkers) {
;     ...
;     float* sTc = (float*)sq;
;     if (wave == 0) {
;       float* mycol = sTc + lane * 68;
; #pragma unroll 1
;       for (int blk = 0; blk < 4; ++blk) {
;         const int r0 = blk * 16;
;         float acc[16];
; #pragma unroll
;         for (int r = 0; r < 16; ++r) acc[r] = 0.f;
; #pragma unroll 1
;         for (int j = 0; j < r0; j += 4) {
;           const float4 t4 = *(const float4*)(mycol + j);
; #pragma unroll
;           for (int r = 0; r < 16; ++r) {
;             const float4 m4 = *(const float4*)(sM + (r0 + r) * 68 + j);
;             acc[r] += (m4.x * t4.x + m4.y * t4.y) + (m4.z * t4.z + m4.w * t4.w);
;           }
;         }
;         float tt[16];
; #pragma unroll
;         for (int r = 0; r < 16; ++r) {
;           float s = acc[r];
; #pragma unroll
;           for (int q4 = 0; q4 < r; q4 += 4) {
;             const float4 m4 = *(const float4*)(sM + (r0 + r) * 68 + r0 + q4);
;             s += m4.x * tt[q4];
;             if (q4 + 1 < r) s += m4.y * tt[q4 + 1];
;             if (q4 + 2 < r) s += m4.z * tt[q4 + 2];
;             if (q4 + 3 < r) s += m4.w * tt[q4 + 3];
;           }
;           tt[r] = ((r0 + r == lane) ? 1.f : 0.f) - s;
;         }
; #pragma unroll
;         for (int r = 0; r < 16; r += 4) *(float4*)(mycol + r0 + r) = make_float4(tt[r], tt[r + 1], tt[r + 2], tt[r + 3]);
;       }
;     }
	s_mov_b64 s[42:43], exec
	v_and_b32_e32 v178, 63, v218
	v_readfirstlane_b32 s68, v218
	v_and_b32_e32 v179, 15, v178
	v_lshrrev_b32_e32 v221, 4, v178
	s_nop 1
	s_lshr_b32 s68, s68, 6
	s_mul_i32 s69, s68, 0x1100
	s_mul_i32 s70, s68, 0x500
	s_lshl_b32 s71, s68, 4
	v_mul_u32_u24_e32 v192, 0x110, v179
	v_mul_u32_u24_e32 v213, 0x50, v179
	v_add_u32_e32 v216, s71, v179
	v_add_u32_e32 v212, s69, v192
	v_add_u32_e32 v212, 0x8610, v212
	v_lshl_add_u32 v192, v221, 2, v192
	v_add_u32_e32 v213, s70, v213
	v_add_u32_e32 v213, 0xca10, v213
	v_add_u32_e32 v193, s69, v192
	v_add_u32_e32 v193, 0x8610, v193
	v_add_u32_e32 v192, 16, v192
	v_lshl_add_u32 v214, v221, 4, v213
	v_mov_b32_e32 v215, 0
	v_mov_b32_e32 v196, 0
	v_mov_b32_e32 v197, 0
	v_mov_b32_e32 v198, 0
	v_mov_b32_e32 v199, 0
	v_mov_b32_e32 v200, 0
	v_mov_b32_e32 v201, 0
	v_mov_b32_e32 v202, 0
	v_mov_b32_e32 v203, 0
	v_mov_b32_e32 v204, 0
	v_mov_b32_e32 v205, 0
	v_mov_b32_e32 v206, 0
	v_mov_b32_e32 v207, 0
	v_mov_b32_e32 v208, 0
	v_mov_b32_e32 v209, 0
	v_mov_b32_e32 v210, 0
	v_mov_b32_e32 v211, 0
	ds_read_b128 v[222:225], v215 offset:288
	v_cmp_eq_u32_e32 vcc, 0, v216
	s_nop 1
	v_cndmask_b32_e64 v178, 0, 1.0, vcc
	v_sub_f32_e32 v196, v178, v196
	ds_read_b128 v[238:241], v215 offset:560
	v_cmp_eq_u32_e32 vcc, 1, v216
	s_waitcnt lgkmcnt(1)
	v_fmac_f32_e32 v197, v222, v196
	s_nop 0
	v_cndmask_b32_e64 v178, 0, 1.0, vcc
	v_sub_f32_e32 v197, v178, v197
	ds_read_b128 v[222:225], v215 offset:832
	v_cmp_eq_u32_e32 vcc, 2, v216
	s_waitcnt lgkmcnt(1)
	v_fmac_f32_e32 v198, v238, v196
	v_fmac_f32_e32 v198, v239, v197
	v_cndmask_b32_e64 v178, 0, 1.0, vcc
	v_sub_f32_e32 v198, v178, v198
	ds_read_b128 v[238:241], v215 offset:1104
	v_cmp_eq_u32_e32 vcc, 3, v216
	s_waitcnt lgkmcnt(1)
	v_fmac_f32_e32 v199, v222, v196
	v_fmac_f32_e32 v199, v223, v197
	v_fmac_f32_e32 v199, v224, v198
	v_cndmask_b32_e64 v178, 0, 1.0, vcc
	v_sub_f32_e32 v199, v178, v199
	ds_read_b128 v[222:225], v215 offset:1376
	ds_read_b128 v[226:229], v215 offset:1392
	v_cmp_eq_u32_e32 vcc, 4, v216
	s_waitcnt lgkmcnt(2)
	v_fmac_f32_e32 v200, v238, v196
	v_fmac_f32_e32 v200, v239, v197
	v_fmac_f32_e32 v200, v240, v198
	v_fmac_f32_e32 v200, v241, v199
	v_cndmask_b32_e64 v178, 0, 1.0, vcc
	v_sub_f32_e32 v200, v178, v200
	ds_read_b128 v[238:241], v215 offset:1648
	ds_read_b128 v[242:245], v215 offset:1664
	v_cmp_eq_u32_e32 vcc, 5, v216
	s_waitcnt lgkmcnt(2)
	v_fmac_f32_e32 v201, v222, v196
	v_fmac_f32_e32 v201, v223, v197
	v_fmac_f32_e32 v201, v224, v198
	v_fmac_f32_e32 v201, v225, v199
	v_fmac_f32_e32 v201, v226, v200
	v_cndmask_b32_e64 v178, 0, 1.0, vcc
	v_sub_f32_e32 v201, v178, v201
	ds_read_b128 v[222:225], v215 offset:1920
	ds_read_b128 v[226:229], v215 offset:1936
	v_cmp_eq_u32_e32 vcc, 6, v216
	s_waitcnt lgkmcnt(2)
	v_fmac_f32_e32 v202, v238, v196
	v_fmac_f32_e32 v202, v239, v197
	v_fmac_f32_e32 v202, v240, v198
	v_fmac_f32_e32 v202, v241, v199
	v_fmac_f32_e32 v202, v242, v200
	v_fmac_f32_e32 v202, v243, v201
	v_cndmask_b32_e64 v178, 0, 1.0, vcc
	v_sub_f32_e32 v202, v178, v202
	ds_read_b128 v[238:241], v215 offset:2192
	ds_read_b128 v[242:245], v215 offset:2208
	v_cmp_eq_u32_e32 vcc, 7, v216
	s_waitcnt lgkmcnt(2)
	v_fmac_f32_e32 v203, v222, v196
	v_fmac_f32_e32 v203, v223, v197
	v_fmac_f32_e32 v203, v224, v198
	v_fmac_f32_e32 v203, v225, v199
	v_fmac_f32_e32 v203, v226, v200
	v_fmac_f32_e32 v203, v227, v201
	v_fmac_f32_e32 v203, v228, v202
	v_cndmask_b32_e64 v178, 0, 1.0, vcc
	v_sub_f32_e32 v203, v178, v203
	ds_read_b128 v[222:225], v215 offset:2464
	ds_read_b128 v[226:229], v215 offset:2480
	ds_read_b128 v[230:233], v215 offset:2496
	v_cmp_eq_u32_e32 vcc, 8, v216
	s_waitcnt lgkmcnt(3)
	v_fmac_f32_e32 v204, v238, v196
	v_fmac_f32_e32 v204, v239, v197
	v_fmac_f32_e32 v204, v240, v198
	v_fmac_f32_e32 v204, v241, v199
	v_fmac_f32_e32 v204, v242, v200
	v_fmac_f32_e32 v204, v243, v201
	v_fmac_f32_e32 v204, v244, v202
	v_fmac_f32_e32 v204, v245, v203
	v_cndmask_b32_e64 v178, 0, 1.0, vcc
	v_sub_f32_e32 v204, v178, v204
	ds_read_b128 v[238:241], v215 offset:2736
	ds_read_b128 v[242:245], v215 offset:2752
	ds_read_b128 v[248:251], v215 offset:2768
	v_cmp_eq_u32_e32 vcc, 9, v216
	s_waitcnt lgkmcnt(3)
	v_fmac_f32_e32 v205, v222, v196
	v_fmac_f32_e32 v205, v223, v197
	v_fmac_f32_e32 v205, v224, v198
	v_fmac_f32_e32 v205, v225, v199
	v_fmac_f32_e32 v205, v226, v200
	v_fmac_f32_e32 v205, v227, v201
	v_fmac_f32_e32 v205, v228, v202
	v_fmac_f32_e32 v205, v229, v203
	v_fmac_f32_e32 v205, v230, v204
	v_cndmask_b32_e64 v178, 0, 1.0, vcc
	v_sub_f32_e32 v205, v178, v205
	ds_read_b128 v[222:225], v215 offset:3008
	ds_read_b128 v[226:229], v215 offset:3024
	ds_read_b128 v[230:233], v215 offset:3040
	v_cmp_eq_u32_e32 vcc, 10, v216
	s_waitcnt lgkmcnt(3)
	v_fmac_f32_e32 v206, v238, v196
	v_fmac_f32_e32 v206, v239, v197
	v_fmac_f32_e32 v206, v240, v198
	v_fmac_f32_e32 v206, v241, v199
	v_fmac_f32_e32 v206, v242, v200
	v_fmac_f32_e32 v206, v243, v201
	v_fmac_f32_e32 v206, v244, v202
	v_fmac_f32_e32 v206, v245, v203
	v_fmac_f32_e32 v206, v248, v204
	v_fmac_f32_e32 v206, v249, v205
	v_cndmask_b32_e64 v178, 0, 1.0, vcc
	v_sub_f32_e32 v206, v178, v206
	ds_read_b128 v[238:241], v215 offset:3280
	ds_read_b128 v[242:245], v215 offset:3296
	ds_read_b128 v[248:251], v215 offset:3312
	v_cmp_eq_u32_e32 vcc, 11, v216
	s_waitcnt lgkmcnt(3)
	v_fmac_f32_e32 v207, v222, v196
	v_fmac_f32_e32 v207, v223, v197
	v_fmac_f32_e32 v207, v224, v198
	v_fmac_f32_e32 v207, v225, v199
	v_fmac_f32_e32 v207, v226, v200
	v_fmac_f32_e32 v207, v227, v201
	v_fmac_f32_e32 v207, v228, v202
	v_fmac_f32_e32 v207, v229, v203
	v_fmac_f32_e32 v207, v230, v204
	v_fmac_f32_e32 v207, v231, v205
	v_fmac_f32_e32 v207, v232, v206
	v_cndmask_b32_e64 v178, 0, 1.0, vcc
	v_sub_f32_e32 v207, v178, v207
	ds_read_b128 v[222:225], v215 offset:3552
	ds_read_b128 v[226:229], v215 offset:3568
	ds_read_b128 v[230:233], v215 offset:3584
	ds_read_b128 v[234:237], v215 offset:3600
	v_cmp_eq_u32_e32 vcc, 12, v216
	s_waitcnt lgkmcnt(4)
; template <bool SIGNAL>
; __device__ __forceinline__ void phase2(const Params& p, unsigned char* smem, const int lo, const int hi, const int worker, const int nworkers) {
;     ...
;     float* sTc = (float*)sq;
;     if (wave == 0) {
;       float* mycol = sTc + lane * 68;
; #pragma unroll 1
;       for (int blk = 0; blk < 4; ++blk) {
;         const int r0 = blk * 16;
;         float acc[16];
; #pragma unroll
;         for (int r = 0; r < 16; ++r) acc[r] = 0.f;
; #pragma unroll 1
;         for (int j = 0; j < r0; j += 4) {
;           const float4 t4 = *(const float4*)(mycol + j);
; #pragma unroll
;           for (int r = 0; r < 16; ++r) {
;             const float4 m4 = *(const float4*)(sM + (r0 + r) * 68 + j);
;             acc[r] += (m4.x * t4.x + m4.y * t4.y) + (m4.z * t4.z + m4.w * t4.w);
;           }
;         }
;         float tt[16];
; #pragma unroll
;         for (int r = 0; r < 16; ++r) {
;           float s = acc[r];
; #pragma unroll
;           for (int q4 = 0; q4 < r; q4 += 4) {
;             const float4 m4 = *(const float4*)(sM + (r0 + r) * 68 + r0 + q4);
;             s += m4.x * tt[q4];
;             if (q4 + 1 < r) s += m4.y * tt[q4 + 1];
;             if (q4 + 2 < r) s += m4.z * tt[q4 + 2];
;             if (q4 + 3 < r) s += m4.w * tt[q4 + 3];
;           }
;           tt[r] = ((r0 + r == lane) ? 1.f : 0.f) - s;
;         }
; #pragma unroll
;         for (int r = 0; r < 16; r += 4) *(float4*)(mycol + r0 + r) = make_float4(tt[r], tt[r + 1], tt[r + 2], tt[r + 3]);
;       }
;     }
	v_fmac_f32_e32 v208, v238, v196
	v_fmac_f32_e32 v208, v239, v197
	v_fmac_f32_e32 v208, v240, v198
	v_fmac_f32_e32 v208, v241, v199
	v_fmac_f32_e32 v208, v242, v200
	v_fmac_f32_e32 v208, v243, v201
	v_fmac_f32_e32 v208, v244, v202
	v_fmac_f32_e32 v208, v245, v203
	v_fmac_f32_e32 v208, v248, v204
	v_fmac_f32_e32 v208, v249, v205
	v_fmac_f32_e32 v208, v250, v206
	v_fmac_f32_e32 v208, v251, v207
	v_cndmask_b32_e64 v178, 0, 1.0, vcc
	v_sub_f32_e32 v208, v178, v208
	ds_read_b128 v[238:241], v215 offset:3824
	ds_read_b128 v[242:245], v215 offset:3840
	ds_read_b128 v[248:251], v215 offset:3856
	ds_read_b128 v[252:255], v215 offset:3872
	v_cmp_eq_u32_e32 vcc, 13, v216
	s_waitcnt lgkmcnt(4)
	v_fmac_f32_e32 v209, v222, v196
	v_fmac_f32_e32 v209, v223, v197
	v_fmac_f32_e32 v209, v224, v198
	v_fmac_f32_e32 v209, v225, v199
	v_fmac_f32_e32 v209, v226, v200
	v_fmac_f32_e32 v209, v227, v201
	v_fmac_f32_e32 v209, v228, v202
	v_fmac_f32_e32 v209, v229, v203
	v_fmac_f32_e32 v209, v230, v204
	v_fmac_f32_e32 v209, v231, v205
	v_fmac_f32_e32 v209, v232, v206
	v_fmac_f32_e32 v209, v233, v207
	v_fmac_f32_e32 v209, v234, v208
	v_cndmask_b32_e64 v178, 0, 1.0, vcc
	v_sub_f32_e32 v209, v178, v209
	ds_read_b128 v[222:225], v215 offset:4096
	ds_read_b128 v[226:229], v215 offset:4112
	ds_read_b128 v[230:233], v215 offset:4128
	ds_read_b128 v[234:237], v215 offset:4144
	v_cmp_eq_u32_e32 vcc, 14, v216
	s_waitcnt lgkmcnt(4)
	v_fmac_f32_e32 v210, v238, v196
	v_fmac_f32_e32 v210, v239, v197
	v_fmac_f32_e32 v210, v240, v198
	v_fmac_f32_e32 v210, v241, v199
	v_fmac_f32_e32 v210, v242, v200
	v_fmac_f32_e32 v210, v243, v201
	v_fmac_f32_e32 v210, v244, v202
	v_fmac_f32_e32 v210, v245, v203
	v_fmac_f32_e32 v210, v248, v204
	v_fmac_f32_e32 v210, v249, v205
	v_fmac_f32_e32 v210, v250, v206
	v_fmac_f32_e32 v210, v251, v207
	v_fmac_f32_e32 v210, v252, v208
	v_fmac_f32_e32 v210, v253, v209
	v_cndmask_b32_e64 v178, 0, 1.0, vcc
	v_sub_f32_e32 v210, v178, v210
	v_cmp_eq_u32_e32 vcc, 15, v216
	s_waitcnt lgkmcnt(0)
	v_fmac_f32_e32 v211, v222, v196
	v_fmac_f32_e32 v211, v223, v197
	v_fmac_f32_e32 v211, v224, v198
	v_fmac_f32_e32 v211, v225, v199
	v_fmac_f32_e32 v211, v226, v200
	v_fmac_f32_e32 v211, v227, v201
	v_fmac_f32_e32 v211, v228, v202
	v_fmac_f32_e32 v211, v229, v203
	v_fmac_f32_e32 v211, v230, v204
	v_fmac_f32_e32 v211, v231, v205
	v_fmac_f32_e32 v211, v232, v206
	v_fmac_f32_e32 v211, v233, v207
	v_fmac_f32_e32 v211, v234, v208
	v_fmac_f32_e32 v211, v235, v209
	v_fmac_f32_e32 v211, v236, v210
	v_cndmask_b32_e64 v178, 0, 1.0, vcc
	v_sub_f32_e32 v211, v178, v211
	ds_write_b128 v212, v[196:199] offset:0
	ds_write_b128 v212, v[200:203] offset:16
	ds_write_b128 v212, v[204:207] offset:32
	ds_write_b128 v212, v[208:211] offset:48
	s_waitcnt lgkmcnt(0)
	ds_read_b32 v222, v192 offset:4352
	ds_read_b32 v238, v193 offset:0
	ds_read_b32 v223, v192 offset:4368
	ds_read_b32 v239, v193 offset:16
	ds_read_b32 v224, v192 offset:4384
	ds_read_b32 v240, v193 offset:32
	ds_read_b32 v225, v192 offset:4400
	ds_read_b32 v241, v193 offset:48
	s_waitcnt lgkmcnt(0)
	v_mfma_f32_16x16x4_f32 v[180:183], v222, v238, 0
	v_mfma_f32_16x16x4_f32 v[180:183], v223, v239, v[180:183]
	v_mfma_f32_16x16x4_f32 v[180:183], v224, v240, v[180:183]
	v_mfma_f32_16x16x4_f32 v[180:183], v225, v241, v[180:183]
	s_nop 7
	s_nop 7
	ds_write_b128 v214, v[180:183]
	s_waitcnt lgkmcnt(0)
	ds_read_b128 v[196:199], v213
	ds_read_b128 v[200:203], v213 offset:16
	ds_read_b128 v[204:207], v213 offset:32
	ds_read_b128 v[208:211], v213 offset:48
	s_waitcnt lgkmcnt(0)
	ds_read_b128 v[222:225], v215 offset:4704
	v_cmp_eq_u32_e32 vcc, 16, v216
	s_nop 1
	v_cndmask_b32_e64 v178, 0, 1.0, vcc
	v_sub_f32_e32 v196, v178, v196
	ds_read_b128 v[238:241], v215 offset:4976
	v_cmp_eq_u32_e32 vcc, 17, v216
	s_waitcnt lgkmcnt(1)
	v_fmac_f32_e32 v197, v222, v196
	s_nop 0
	v_cndmask_b32_e64 v178, 0, 1.0, vcc
	v_sub_f32_e32 v197, v178, v197
	ds_read_b128 v[222:225], v215 offset:5248
	v_cmp_eq_u32_e32 vcc, 18, v216
	s_waitcnt lgkmcnt(1)
	v_fmac_f32_e32 v198, v238, v196
	v_fmac_f32_e32 v198, v239, v197
	v_cndmask_b32_e64 v178, 0, 1.0, vcc
	v_sub_f32_e32 v198, v178, v198
	ds_read_b128 v[238:241], v215 offset:5520
	v_cmp_eq_u32_e32 vcc, 19, v216
	s_waitcnt lgkmcnt(1)
	v_fmac_f32_e32 v199, v222, v196
	v_fmac_f32_e32 v199, v223, v197
	v_fmac_f32_e32 v199, v224, v198
	v_cndmask_b32_e64 v178, 0, 1.0, vcc
	v_sub_f32_e32 v199, v178, v199
	ds_read_b128 v[222:225], v215 offset:5792
	ds_read_b128 v[226:229], v215 offset:5808
	v_cmp_eq_u32_e32 vcc, 20, v216
	s_waitcnt lgkmcnt(2)
	v_fmac_f32_e32 v200, v238, v196
	v_fmac_f32_e32 v200, v239, v197
	v_fmac_f32_e32 v200, v240, v198
	v_fmac_f32_e32 v200, v241, v199
	v_cndmask_b32_e64 v178, 0, 1.0, vcc
	v_sub_f32_e32 v200, v178, v200
	ds_read_b128 v[238:241], v215 offset:6064
	ds_read_b128 v[242:245], v215 offset:6080
	v_cmp_eq_u32_e32 vcc, 21, v216
	s_waitcnt lgkmcnt(2)
	v_fmac_f32_e32 v201, v222, v196
	v_fmac_f32_e32 v201, v223, v197
	v_fmac_f32_e32 v201, v224, v198
	v_fmac_f32_e32 v201, v225, v199
	v_fmac_f32_e32 v201, v226, v200
	v_cndmask_b32_e64 v178, 0, 1.0, vcc
	v_sub_f32_e32 v201, v178, v201
	ds_read_b128 v[222:225], v215 offset:6336
	ds_read_b128 v[226:229], v215 offset:6352
	v_cmp_eq_u32_e32 vcc, 22, v216
	s_waitcnt lgkmcnt(2)
	v_fmac_f32_e32 v202, v238, v196
	v_fmac_f32_e32 v202, v239, v197
	v_fmac_f32_e32 v202, v240, v198
	v_fmac_f32_e32 v202, v241, v199
	v_fmac_f32_e32 v202, v242, v200
	v_fmac_f32_e32 v202, v243, v201
	v_cndmask_b32_e64 v178, 0, 1.0, vcc
	v_sub_f32_e32 v202, v178, v202
	ds_read_b128 v[238:241], v215 offset:6608
	ds_read_b128 v[242:245], v215 offset:6624
	v_cmp_eq_u32_e32 vcc, 23, v216
	s_waitcnt lgkmcnt(2)
; template <bool SIGNAL>
; __device__ __forceinline__ void phase2(const Params& p, unsigned char* smem, const int lo, const int hi, const int worker, const int nworkers) {
;     ...
;     float* sTc = (float*)sq;
;     if (wave == 0) {
;       float* mycol = sTc + lane * 68;
; #pragma unroll 1
;       for (int blk = 0; blk < 4; ++blk) {
;         const int r0 = blk * 16;
;         float acc[16];
; #pragma unroll
;         for (int r = 0; r < 16; ++r) acc[r] = 0.f;
; #pragma unroll 1
;         for (int j = 0; j < r0; j += 4) {
;           const float4 t4 = *(const float4*)(mycol + j);
; #pragma unroll
;           for (int r = 0; r < 16; ++r) {
;             const float4 m4 = *(const float4*)(sM + (r0 + r) * 68 + j);
;             acc[r] += (m4.x * t4.x + m4.y * t4.y) + (m4.z * t4.z + m4.w * t4.w);
;           }
;         }
;         float tt[16];
; #pragma unroll
;         for (int r = 0; r < 16; ++r) {
;           float s = acc[r];
; #pragma unroll
;           for (int q4 = 0; q4 < r; q4 += 4) {
;             const float4 m4 = *(const float4*)(sM + (r0 + r) * 68 + r0 + q4);
;             s += m4.x * tt[q4];
;             if (q4 + 1 < r) s += m4.y * tt[q4 + 1];
;             if (q4 + 2 < r) s += m4.z * tt[q4 + 2];
;             if (q4 + 3 < r) s += m4.w * tt[q4 + 3];
;           }
;           tt[r] = ((r0 + r == lane) ? 1.f : 0.f) - s;
;         }
; #pragma unroll
;         for (int r = 0; r < 16; r += 4) *(float4*)(mycol + r0 + r) = make_float4(tt[r], tt[r + 1], tt[r + 2], tt[r + 3]);
;       }
;     }
	v_fmac_f32_e32 v203, v222, v196
	v_fmac_f32_e32 v203, v223, v197
	v_fmac_f32_e32 v203, v224, v198
	v_fmac_f32_e32 v203, v225, v199
	v_fmac_f32_e32 v203, v226, v200
	v_fmac_f32_e32 v203, v227, v201
	v_fmac_f32_e32 v203, v228, v202
	v_cndmask_b32_e64 v178, 0, 1.0, vcc
	v_sub_f32_e32 v203, v178, v203
	ds_read_b128 v[222:225], v215 offset:6880
	ds_read_b128 v[226:229], v215 offset:6896
	ds_read_b128 v[230:233], v215 offset:6912
	v_cmp_eq_u32_e32 vcc, 24, v216
	s_waitcnt lgkmcnt(3)
	v_fmac_f32_e32 v204, v238, v196
	v_fmac_f32_e32 v204, v239, v197
	v_fmac_f32_e32 v204, v240, v198
	v_fmac_f32_e32 v204, v241, v199
	v_fmac_f32_e32 v204, v242, v200
	v_fmac_f32_e32 v204, v243, v201
	v_fmac_f32_e32 v204, v244, v202
	v_fmac_f32_e32 v204, v245, v203
	v_cndmask_b32_e64 v178, 0, 1.0, vcc
	v_sub_f32_e32 v204, v178, v204
	ds_read_b128 v[238:241], v215 offset:7152
	ds_read_b128 v[242:245], v215 offset:7168
	ds_read_b128 v[248:251], v215 offset:7184
	v_cmp_eq_u32_e32 vcc, 25, v216
	s_waitcnt lgkmcnt(3)
	v_fmac_f32_e32 v205, v222, v196
	v_fmac_f32_e32 v205, v223, v197
	v_fmac_f32_e32 v205, v224, v198
	v_fmac_f32_e32 v205, v225, v199
	v_fmac_f32_e32 v205, v226, v200
	v_fmac_f32_e32 v205, v227, v201
	v_fmac_f32_e32 v205, v228, v202
	v_fmac_f32_e32 v205, v229, v203
	v_fmac_f32_e32 v205, v230, v204
	v_cndmask_b32_e64 v178, 0, 1.0, vcc
	v_sub_f32_e32 v205, v178, v205
	ds_read_b128 v[222:225], v215 offset:7424
	ds_read_b128 v[226:229], v215 offset:7440
	ds_read_b128 v[230:233], v215 offset:7456
	v_cmp_eq_u32_e32 vcc, 26, v216
	s_waitcnt lgkmcnt(3)
	v_fmac_f32_e32 v206, v238, v196
	v_fmac_f32_e32 v206, v239, v197
	v_fmac_f32_e32 v206, v240, v198
	v_fmac_f32_e32 v206, v241, v199
	v_fmac_f32_e32 v206, v242, v200
	v_fmac_f32_e32 v206, v243, v201
	v_fmac_f32_e32 v206, v244, v202
	v_fmac_f32_e32 v206, v245, v203
	v_fmac_f32_e32 v206, v248, v204
	v_fmac_f32_e32 v206, v249, v205
	v_cndmask_b32_e64 v178, 0, 1.0, vcc
	v_sub_f32_e32 v206, v178, v206
	ds_read_b128 v[238:241], v215 offset:7696
	ds_read_b128 v[242:245], v215 offset:7712
	ds_read_b128 v[248:251], v215 offset:7728
	v_cmp_eq_u32_e32 vcc, 27, v216
	s_waitcnt lgkmcnt(3)
	v_fmac_f32_e32 v207, v222, v196
	v_fmac_f32_e32 v207, v223, v197
	v_fmac_f32_e32 v207, v224, v198
	v_fmac_f32_e32 v207, v225, v199
	v_fmac_f32_e32 v207, v226, v200
	v_fmac_f32_e32 v207, v227, v201
	v_fmac_f32_e32 v207, v228, v202
	v_fmac_f32_e32 v207, v229, v203
	v_fmac_f32_e32 v207, v230, v204
	v_fmac_f32_e32 v207, v231, v205
	v_fmac_f32_e32 v207, v232, v206
	v_cndmask_b32_e64 v178, 0, 1.0, vcc
	v_sub_f32_e32 v207, v178, v207
	ds_read_b128 v[222:225], v215 offset:7968
	ds_read_b128 v[226:229], v215 offset:7984
	ds_read_b128 v[230:233], v215 offset:8000
	ds_read_b128 v[234:237], v215 offset:8016
	v_cmp_eq_u32_e32 vcc, 28, v216
	s_waitcnt lgkmcnt(4)
	v_fmac_f32_e32 v208, v238, v196
	v_fmac_f32_e32 v208, v239, v197
	v_fmac_f32_e32 v208, v240, v198
	v_fmac_f32_e32 v208, v241, v199
	v_fmac_f32_e32 v208, v242, v200
	v_fmac_f32_e32 v208, v243, v201
	v_fmac_f32_e32 v208, v244, v202
	v_fmac_f32_e32 v208, v245, v203
	v_fmac_f32_e32 v208, v248, v204
	v_fmac_f32_e32 v208, v249, v205
	v_fmac_f32_e32 v208, v250, v206
	v_fmac_f32_e32 v208, v251, v207
	v_cndmask_b32_e64 v178, 0, 1.0, vcc
	v_sub_f32_e32 v208, v178, v208
	ds_read_b128 v[238:241], v215 offset:8240
	ds_read_b128 v[242:245], v215 offset:8256
	ds_read_b128 v[248:251], v215 offset:8272
	ds_read_b128 v[252:255], v215 offset:8288
	v_cmp_eq_u32_e32 vcc, 29, v216
	s_waitcnt lgkmcnt(4)
	v_fmac_f32_e32 v209, v222, v196
	v_fmac_f32_e32 v209, v223, v197
	v_fmac_f32_e32 v209, v224, v198
	v_fmac_f32_e32 v209, v225, v199
	v_fmac_f32_e32 v209, v226, v200
	v_fmac_f32_e32 v209, v227, v201
	v_fmac_f32_e32 v209, v228, v202
	v_fmac_f32_e32 v209, v229, v203
	v_fmac_f32_e32 v209, v230, v204
	v_fmac_f32_e32 v209, v231, v205
	v_fmac_f32_e32 v209, v232, v206
	v_fmac_f32_e32 v209, v233, v207
	v_fmac_f32_e32 v209, v234, v208
	v_cndmask_b32_e64 v178, 0, 1.0, vcc
	v_sub_f32_e32 v209, v178, v209
	ds_read_b128 v[222:225], v215 offset:8512
	ds_read_b128 v[226:229], v215 offset:8528
	ds_read_b128 v[230:233], v215 offset:8544
	ds_read_b128 v[234:237], v215 offset:8560
	v_cmp_eq_u32_e32 vcc, 30, v216
	s_waitcnt lgkmcnt(4)
	v_fmac_f32_e32 v210, v238, v196
	v_fmac_f32_e32 v210, v239, v197
	v_fmac_f32_e32 v210, v240, v198
	v_fmac_f32_e32 v210, v241, v199
	v_fmac_f32_e32 v210, v242, v200
	v_fmac_f32_e32 v210, v243, v201
	v_fmac_f32_e32 v210, v244, v202
	v_fmac_f32_e32 v210, v245, v203
	v_fmac_f32_e32 v210, v248, v204
	v_fmac_f32_e32 v210, v249, v205
	v_fmac_f32_e32 v210, v250, v206
	v_fmac_f32_e32 v210, v251, v207
	v_fmac_f32_e32 v210, v252, v208
	v_fmac_f32_e32 v210, v253, v209
	v_cndmask_b32_e64 v178, 0, 1.0, vcc
	v_sub_f32_e32 v210, v178, v210
	v_cmp_eq_u32_e32 vcc, 31, v216
	s_waitcnt lgkmcnt(0)
	v_fmac_f32_e32 v211, v222, v196
	v_fmac_f32_e32 v211, v223, v197
	v_fmac_f32_e32 v211, v224, v198
	v_fmac_f32_e32 v211, v225, v199
	v_fmac_f32_e32 v211, v226, v200
	v_fmac_f32_e32 v211, v227, v201
	v_fmac_f32_e32 v211, v228, v202
	v_fmac_f32_e32 v211, v229, v203
	v_fmac_f32_e32 v211, v230, v204
	v_fmac_f32_e32 v211, v231, v205
	v_fmac_f32_e32 v211, v232, v206
	v_fmac_f32_e32 v211, v233, v207
	v_fmac_f32_e32 v211, v234, v208
	v_fmac_f32_e32 v211, v235, v209
	v_fmac_f32_e32 v211, v236, v210
	v_cndmask_b32_e64 v178, 0, 1.0, vcc
	v_sub_f32_e32 v211, v178, v211
	ds_write_b128 v212, v[196:199] offset:64
	ds_write_b128 v212, v[200:203] offset:80
	ds_write_b128 v212, v[204:207] offset:96
	ds_write_b128 v212, v[208:211] offset:112
	s_waitcnt lgkmcnt(0)
; template <bool SIGNAL>
; __device__ __forceinline__ void phase2(const Params& p, unsigned char* smem, const int lo, const int hi, const int worker, const int nworkers) {
;     ...
;     float* sTc = (float*)sq;
;     if (wave == 0) {
;       float* mycol = sTc + lane * 68;
; #pragma unroll 1
;       for (int blk = 0; blk < 4; ++blk) {
;         const int r0 = blk * 16;
;         float acc[16];
; #pragma unroll
;         for (int r = 0; r < 16; ++r) acc[r] = 0.f;
; #pragma unroll 1
;         for (int j = 0; j < r0; j += 4) {
;           const float4 t4 = *(const float4*)(mycol + j);
; #pragma unroll
;           for (int r = 0; r < 16; ++r) {
;             const float4 m4 = *(const float4*)(sM + (r0 + r) * 68 + j);
;             acc[r] += (m4.x * t4.x + m4.y * t4.y) + (m4.z * t4.z + m4.w * t4.w);
;           }
;         }
;         float tt[16];
; #pragma unroll
;         for (int r = 0; r < 16; ++r) {
;           float s = acc[r];
; #pragma unroll
;           for (int q4 = 0; q4 < r; q4 += 4) {
;             const float4 m4 = *(const float4*)(sM + (r0 + r) * 68 + r0 + q4);
;             s += m4.x * tt[q4];
;             if (q4 + 1 < r) s += m4.y * tt[q4 + 1];
;             if (q4 + 2 < r) s += m4.z * tt[q4 + 2];
;             if (q4 + 3 < r) s += m4.w * tt[q4 + 3];
;           }
;           tt[r] = ((r0 + r == lane) ? 1.f : 0.f) - s;
;         }
; #pragma unroll
;         for (int r = 0; r < 16; r += 4) *(float4*)(mycol + r0 + r) = make_float4(tt[r], tt[r + 1], tt[r + 2], tt[r + 3]);
;       }
;     }
	ds_read_b32 v222, v192 offset:8704
	ds_read_b32 v238, v193 offset:0
	ds_read_b32 v223, v192 offset:8720
	ds_read_b32 v239, v193 offset:16
	ds_read_b32 v224, v192 offset:8736
	ds_read_b32 v240, v193 offset:32
	ds_read_b32 v225, v192 offset:8752
	ds_read_b32 v241, v193 offset:48
	ds_read_b32 v226, v192 offset:8768
	ds_read_b32 v242, v193 offset:64
	ds_read_b32 v227, v192 offset:8784
	ds_read_b32 v243, v193 offset:80
	s_waitcnt lgkmcnt(0)
	v_mfma_f32_16x16x4_f32 v[180:183], v222, v238, 0
	v_mfma_f32_16x16x4_f32 v[180:183], v223, v239, v[180:183]
	v_mfma_f32_16x16x4_f32 v[180:183], v224, v240, v[180:183]
	v_mfma_f32_16x16x4_f32 v[180:183], v225, v241, v[180:183]
	v_mfma_f32_16x16x4_f32 v[180:183], v226, v242, v[180:183]
	v_mfma_f32_16x16x4_f32 v[180:183], v227, v243, v[180:183]
	ds_read_b32 v228, v192 offset:8800
	ds_read_b32 v244, v193 offset:96
	ds_read_b32 v229, v192 offset:8816
	ds_read_b32 v245, v193 offset:112
	s_waitcnt lgkmcnt(0)
	v_mfma_f32_16x16x4_f32 v[180:183], v228, v244, v[180:183]
	v_mfma_f32_16x16x4_f32 v[180:183], v229, v245, v[180:183]
	s_nop 7
	s_nop 7
	ds_write_b128 v214, v[180:183]
	s_waitcnt lgkmcnt(0)
	ds_read_b128 v[196:199], v213
	ds_read_b128 v[200:203], v213 offset:16
	ds_read_b128 v[204:207], v213 offset:32
	ds_read_b128 v[208:211], v213 offset:48
	s_waitcnt lgkmcnt(0)
	ds_read_b128 v[222:225], v215 offset:9120
	v_cmp_eq_u32_e32 vcc, 32, v216
	s_nop 1
	v_cndmask_b32_e64 v178, 0, 1.0, vcc
	v_sub_f32_e32 v196, v178, v196
	ds_read_b128 v[238:241], v215 offset:9392
	v_cmp_eq_u32_e32 vcc, 33, v216
	s_waitcnt lgkmcnt(1)
	v_fmac_f32_e32 v197, v222, v196
	s_nop 0
	v_cndmask_b32_e64 v178, 0, 1.0, vcc
	v_sub_f32_e32 v197, v178, v197
	ds_read_b128 v[222:225], v215 offset:9664
	v_cmp_eq_u32_e32 vcc, 34, v216
	s_waitcnt lgkmcnt(1)
	v_fmac_f32_e32 v198, v238, v196
	v_fmac_f32_e32 v198, v239, v197
	v_cndmask_b32_e64 v178, 0, 1.0, vcc
	v_sub_f32_e32 v198, v178, v198
	ds_read_b128 v[238:241], v215 offset:9936
	v_cmp_eq_u32_e32 vcc, 35, v216
	s_waitcnt lgkmcnt(1)
	v_fmac_f32_e32 v199, v222, v196
	v_fmac_f32_e32 v199, v223, v197
	v_fmac_f32_e32 v199, v224, v198
	v_cndmask_b32_e64 v178, 0, 1.0, vcc
	v_sub_f32_e32 v199, v178, v199
	ds_read_b128 v[222:225], v215 offset:10208
	ds_read_b128 v[226:229], v215 offset:10224
	v_cmp_eq_u32_e32 vcc, 36, v216
	s_waitcnt lgkmcnt(2)
	v_fmac_f32_e32 v200, v238, v196
	v_fmac_f32_e32 v200, v239, v197
	v_fmac_f32_e32 v200, v240, v198
	v_fmac_f32_e32 v200, v241, v199
	v_cndmask_b32_e64 v178, 0, 1.0, vcc
	v_sub_f32_e32 v200, v178, v200
	ds_read_b128 v[238:241], v215 offset:10480
	ds_read_b128 v[242:245], v215 offset:10496
	v_cmp_eq_u32_e32 vcc, 37, v216
	s_waitcnt lgkmcnt(2)
	v_fmac_f32_e32 v201, v222, v196
	v_fmac_f32_e32 v201, v223, v197
	v_fmac_f32_e32 v201, v224, v198
	v_fmac_f32_e32 v201, v225, v199
	v_fmac_f32_e32 v201, v226, v200
	v_cndmask_b32_e64 v178, 0, 1.0, vcc
	v_sub_f32_e32 v201, v178, v201
	ds_read_b128 v[222:225], v215 offset:10752
	ds_read_b128 v[226:229], v215 offset:10768
	v_cmp_eq_u32_e32 vcc, 38, v216
	s_waitcnt lgkmcnt(2)
	v_fmac_f32_e32 v202, v238, v196
	v_fmac_f32_e32 v202, v239, v197
	v_fmac_f32_e32 v202, v240, v198
	v_fmac_f32_e32 v202, v241, v199
	v_fmac_f32_e32 v202, v242, v200
	v_fmac_f32_e32 v202, v243, v201
	v_cndmask_b32_e64 v178, 0, 1.0, vcc
	v_sub_f32_e32 v202, v178, v202
	ds_read_b128 v[238:241], v215 offset:11024
	ds_read_b128 v[242:245], v215 offset:11040
	v_cmp_eq_u32_e32 vcc, 39, v216
	s_waitcnt lgkmcnt(2)
	v_fmac_f32_e32 v203, v222, v196
	v_fmac_f32_e32 v203, v223, v197
	v_fmac_f32_e32 v203, v224, v198
	v_fmac_f32_e32 v203, v225, v199
	v_fmac_f32_e32 v203, v226, v200
	v_fmac_f32_e32 v203, v227, v201
	v_fmac_f32_e32 v203, v228, v202
	v_cndmask_b32_e64 v178, 0, 1.0, vcc
	v_sub_f32_e32 v203, v178, v203
	ds_read_b128 v[222:225], v215 offset:11296
	ds_read_b128 v[226:229], v215 offset:11312
	ds_read_b128 v[230:233], v215 offset:11328
	v_cmp_eq_u32_e32 vcc, 40, v216
	s_waitcnt lgkmcnt(3)
	v_fmac_f32_e32 v204, v238, v196
	v_fmac_f32_e32 v204, v239, v197
	v_fmac_f32_e32 v204, v240, v198
	v_fmac_f32_e32 v204, v241, v199
	v_fmac_f32_e32 v204, v242, v200
	v_fmac_f32_e32 v204, v243, v201
	v_fmac_f32_e32 v204, v244, v202
	v_fmac_f32_e32 v204, v245, v203
	v_cndmask_b32_e64 v178, 0, 1.0, vcc
	v_sub_f32_e32 v204, v178, v204
	ds_read_b128 v[238:241], v215 offset:11568
	ds_read_b128 v[242:245], v215 offset:11584
	ds_read_b128 v[248:251], v215 offset:11600
	v_cmp_eq_u32_e32 vcc, 41, v216
	s_waitcnt lgkmcnt(3)
	v_fmac_f32_e32 v205, v222, v196
	v_fmac_f32_e32 v205, v223, v197
	v_fmac_f32_e32 v205, v224, v198
	v_fmac_f32_e32 v205, v225, v199
	v_fmac_f32_e32 v205, v226, v200
	v_fmac_f32_e32 v205, v227, v201
	v_fmac_f32_e32 v205, v228, v202
	v_fmac_f32_e32 v205, v229, v203
	v_fmac_f32_e32 v205, v230, v204
	v_cndmask_b32_e64 v178, 0, 1.0, vcc
	v_sub_f32_e32 v205, v178, v205
	ds_read_b128 v[222:225], v215 offset:11840
	ds_read_b128 v[226:229], v215 offset:11856
	ds_read_b128 v[230:233], v215 offset:11872
	v_cmp_eq_u32_e32 vcc, 42, v216
	s_waitcnt lgkmcnt(3)
	v_fmac_f32_e32 v206, v238, v196
	v_fmac_f32_e32 v206, v239, v197
	v_fmac_f32_e32 v206, v240, v198
	v_fmac_f32_e32 v206, v241, v199
	v_fmac_f32_e32 v206, v242, v200
	v_fmac_f32_e32 v206, v243, v201
	v_fmac_f32_e32 v206, v244, v202
	v_fmac_f32_e32 v206, v245, v203
	v_fmac_f32_e32 v206, v248, v204
	v_fmac_f32_e32 v206, v249, v205
	v_cndmask_b32_e64 v178, 0, 1.0, vcc
	v_sub_f32_e32 v206, v178, v206
	ds_read_b128 v[238:241], v215 offset:12112
	ds_read_b128 v[242:245], v215 offset:12128
	ds_read_b128 v[248:251], v215 offset:12144
	v_cmp_eq_u32_e32 vcc, 43, v216
	s_waitcnt lgkmcnt(3)
; template <bool SIGNAL>
; __device__ __forceinline__ void phase2(const Params& p, unsigned char* smem, const int lo, const int hi, const int worker, const int nworkers) {
;     ...
;     float* sTc = (float*)sq;
;     if (wave == 0) {
;       float* mycol = sTc + lane * 68;
; #pragma unroll 1
;       for (int blk = 0; blk < 4; ++blk) {
;         const int r0 = blk * 16;
;         float acc[16];
; #pragma unroll
;         for (int r = 0; r < 16; ++r) acc[r] = 0.f;
; #pragma unroll 1
;         for (int j = 0; j < r0; j += 4) {
;           const float4 t4 = *(const float4*)(mycol + j);
; #pragma unroll
;           for (int r = 0; r < 16; ++r) {
;             const float4 m4 = *(const float4*)(sM + (r0 + r) * 68 + j);
;             acc[r] += (m4.x * t4.x + m4.y * t4.y) + (m4.z * t4.z + m4.w * t4.w);
;           }
;         }
;         float tt[16];
; #pragma unroll
;         for (int r = 0; r < 16; ++r) {
;           float s = acc[r];
; #pragma unroll
;           for (int q4 = 0; q4 < r; q4 += 4) {
;             const float4 m4 = *(const float4*)(sM + (r0 + r) * 68 + r0 + q4);
;             s += m4.x * tt[q4];
;             if (q4 + 1 < r) s += m4.y * tt[q4 + 1];
;             if (q4 + 2 < r) s += m4.z * tt[q4 + 2];
;             if (q4 + 3 < r) s += m4.w * tt[q4 + 3];
;           }
;           tt[r] = ((r0 + r == lane) ? 1.f : 0.f) - s;
;         }
; #pragma unroll
;         for (int r = 0; r < 16; r += 4) *(float4*)(mycol + r0 + r) = make_float4(tt[r], tt[r + 1], tt[r + 2], tt[r + 3]);
;       }
;     }
	v_fmac_f32_e32 v207, v222, v196
	v_fmac_f32_e32 v207, v223, v197
	v_fmac_f32_e32 v207, v224, v198
	v_fmac_f32_e32 v207, v225, v199
	v_fmac_f32_e32 v207, v226, v200
	v_fmac_f32_e32 v207, v227, v201
	v_fmac_f32_e32 v207, v228, v202
	v_fmac_f32_e32 v207, v229, v203
	v_fmac_f32_e32 v207, v230, v204
	v_fmac_f32_e32 v207, v231, v205
	v_fmac_f32_e32 v207, v232, v206
	v_cndmask_b32_e64 v178, 0, 1.0, vcc
	v_sub_f32_e32 v207, v178, v207
	ds_read_b128 v[222:225], v215 offset:12384
	ds_read_b128 v[226:229], v215 offset:12400
	ds_read_b128 v[230:233], v215 offset:12416
	ds_read_b128 v[234:237], v215 offset:12432
	v_cmp_eq_u32_e32 vcc, 44, v216
	s_waitcnt lgkmcnt(4)
	v_fmac_f32_e32 v208, v238, v196
	v_fmac_f32_e32 v208, v239, v197
	v_fmac_f32_e32 v208, v240, v198
	v_fmac_f32_e32 v208, v241, v199
	v_fmac_f32_e32 v208, v242, v200
	v_fmac_f32_e32 v208, v243, v201
	v_fmac_f32_e32 v208, v244, v202
	v_fmac_f32_e32 v208, v245, v203
	v_fmac_f32_e32 v208, v248, v204
	v_fmac_f32_e32 v208, v249, v205
	v_fmac_f32_e32 v208, v250, v206
	v_fmac_f32_e32 v208, v251, v207
	v_cndmask_b32_e64 v178, 0, 1.0, vcc
	v_sub_f32_e32 v208, v178, v208
	ds_read_b128 v[238:241], v215 offset:12656
	ds_read_b128 v[242:245], v215 offset:12672
	ds_read_b128 v[248:251], v215 offset:12688
	ds_read_b128 v[252:255], v215 offset:12704
	v_cmp_eq_u32_e32 vcc, 45, v216
	s_waitcnt lgkmcnt(4)
	v_fmac_f32_e32 v209, v222, v196
	v_fmac_f32_e32 v209, v223, v197
	v_fmac_f32_e32 v209, v224, v198
	v_fmac_f32_e32 v209, v225, v199
	v_fmac_f32_e32 v209, v226, v200
	v_fmac_f32_e32 v209, v227, v201
	v_fmac_f32_e32 v209, v228, v202
	v_fmac_f32_e32 v209, v229, v203
	v_fmac_f32_e32 v209, v230, v204
	v_fmac_f32_e32 v209, v231, v205
	v_fmac_f32_e32 v209, v232, v206
	v_fmac_f32_e32 v209, v233, v207
	v_fmac_f32_e32 v209, v234, v208
	v_cndmask_b32_e64 v178, 0, 1.0, vcc
	v_sub_f32_e32 v209, v178, v209
	ds_read_b128 v[222:225], v215 offset:12928
	ds_read_b128 v[226:229], v215 offset:12944
	ds_read_b128 v[230:233], v215 offset:12960
	ds_read_b128 v[234:237], v215 offset:12976
	v_cmp_eq_u32_e32 vcc, 46, v216
	s_waitcnt lgkmcnt(4)
	v_fmac_f32_e32 v210, v238, v196
	v_fmac_f32_e32 v210, v239, v197
	v_fmac_f32_e32 v210, v240, v198
	v_fmac_f32_e32 v210, v241, v199
	v_fmac_f32_e32 v210, v242, v200
	v_fmac_f32_e32 v210, v243, v201
	v_fmac_f32_e32 v210, v244, v202
	v_fmac_f32_e32 v210, v245, v203
	v_fmac_f32_e32 v210, v248, v204
	v_fmac_f32_e32 v210, v249, v205
	v_fmac_f32_e32 v210, v250, v206
	v_fmac_f32_e32 v210, v251, v207
	v_fmac_f32_e32 v210, v252, v208
	v_fmac_f32_e32 v210, v253, v209
	v_cndmask_b32_e64 v178, 0, 1.0, vcc
	v_sub_f32_e32 v210, v178, v210
	v_cmp_eq_u32_e32 vcc, 47, v216
	s_waitcnt lgkmcnt(0)
	v_fmac_f32_e32 v211, v222, v196
	v_fmac_f32_e32 v211, v223, v197
	v_fmac_f32_e32 v211, v224, v198
	v_fmac_f32_e32 v211, v225, v199
	v_fmac_f32_e32 v211, v226, v200
	v_fmac_f32_e32 v211, v227, v201
	v_fmac_f32_e32 v211, v228, v202
	v_fmac_f32_e32 v211, v229, v203
	v_fmac_f32_e32 v211, v230, v204
	v_fmac_f32_e32 v211, v231, v205
	v_fmac_f32_e32 v211, v232, v206
	v_fmac_f32_e32 v211, v233, v207
	v_fmac_f32_e32 v211, v234, v208
	v_fmac_f32_e32 v211, v235, v209
	v_fmac_f32_e32 v211, v236, v210
	v_cndmask_b32_e64 v178, 0, 1.0, vcc
	v_sub_f32_e32 v211, v178, v211
	ds_write_b128 v212, v[196:199] offset:128
	ds_write_b128 v212, v[200:203] offset:144
	ds_write_b128 v212, v[204:207] offset:160
	ds_write_b128 v212, v[208:211] offset:176
	s_waitcnt lgkmcnt(0)
	ds_read_b32 v222, v192 offset:13056
	ds_read_b32 v238, v193 offset:0
	ds_read_b32 v223, v192 offset:13072
	ds_read_b32 v239, v193 offset:16
	ds_read_b32 v224, v192 offset:13088
	ds_read_b32 v240, v193 offset:32
	ds_read_b32 v225, v192 offset:13104
	ds_read_b32 v241, v193 offset:48
	ds_read_b32 v226, v192 offset:13120
	ds_read_b32 v242, v193 offset:64
	ds_read_b32 v227, v192 offset:13136
	ds_read_b32 v243, v193 offset:80
	s_waitcnt lgkmcnt(0)
	v_mfma_f32_16x16x4_f32 v[180:183], v222, v238, 0
	v_mfma_f32_16x16x4_f32 v[180:183], v223, v239, v[180:183]
	v_mfma_f32_16x16x4_f32 v[180:183], v224, v240, v[180:183]
	v_mfma_f32_16x16x4_f32 v[180:183], v225, v241, v[180:183]
	v_mfma_f32_16x16x4_f32 v[180:183], v226, v242, v[180:183]
	v_mfma_f32_16x16x4_f32 v[180:183], v227, v243, v[180:183]
	ds_read_b32 v228, v192 offset:13152
	ds_read_b32 v244, v193 offset:96
	ds_read_b32 v229, v192 offset:13168
	ds_read_b32 v245, v193 offset:112
	ds_read_b32 v230, v192 offset:13184
	ds_read_b32 v248, v193 offset:128
	ds_read_b32 v231, v192 offset:13200
	ds_read_b32 v249, v193 offset:144
	ds_read_b32 v232, v192 offset:13216
	ds_read_b32 v250, v193 offset:160
	ds_read_b32 v233, v192 offset:13232
	ds_read_b32 v251, v193 offset:176
	s_waitcnt lgkmcnt(0)
	v_mfma_f32_16x16x4_f32 v[180:183], v228, v244, v[180:183]
	v_mfma_f32_16x16x4_f32 v[180:183], v229, v245, v[180:183]
	v_mfma_f32_16x16x4_f32 v[180:183], v230, v248, v[180:183]
	v_mfma_f32_16x16x4_f32 v[180:183], v231, v249, v[180:183]
	v_mfma_f32_16x16x4_f32 v[180:183], v232, v250, v[180:183]
	v_mfma_f32_16x16x4_f32 v[180:183], v233, v251, v[180:183]
	s_nop 7
	s_nop 7
	ds_write_b128 v214, v[180:183]
	s_waitcnt lgkmcnt(0)
	ds_read_b128 v[196:199], v213
	ds_read_b128 v[200:203], v213 offset:16
	ds_read_b128 v[204:207], v213 offset:32
	ds_read_b128 v[208:211], v213 offset:48
	s_waitcnt lgkmcnt(0)
	ds_read_b128 v[222:225], v215 offset:13536
	v_cmp_eq_u32_e32 vcc, 48, v216
	s_nop 1
	v_cndmask_b32_e64 v178, 0, 1.0, vcc
	v_sub_f32_e32 v196, v178, v196
	ds_read_b128 v[238:241], v215 offset:13808
	v_cmp_eq_u32_e32 vcc, 49, v216
	s_waitcnt lgkmcnt(1)
	v_fmac_f32_e32 v197, v222, v196
	s_nop 0
	v_cndmask_b32_e64 v178, 0, 1.0, vcc
	v_sub_f32_e32 v197, v178, v197
	ds_read_b128 v[222:225], v215 offset:14080
	v_cmp_eq_u32_e32 vcc, 50, v216
	s_waitcnt lgkmcnt(1)
; template <bool SIGNAL>
; __device__ __forceinline__ void phase2(const Params& p, unsigned char* smem, const int lo, const int hi, const int worker, const int nworkers) {
;     ...
;     float* sTc = (float*)sq;
;     if (wave == 0) {
;       float* mycol = sTc + lane * 68;
; #pragma unroll 1
;       for (int blk = 0; blk < 4; ++blk) {
;         const int r0 = blk * 16;
;         float acc[16];
; #pragma unroll
;         for (int r = 0; r < 16; ++r) acc[r] = 0.f;
; #pragma unroll 1
;         for (int j = 0; j < r0; j += 4) {
;           const float4 t4 = *(const float4*)(mycol + j);
; #pragma unroll
;           for (int r = 0; r < 16; ++r) {
;             const float4 m4 = *(const float4*)(sM + (r0 + r) * 68 + j);
;             acc[r] += (m4.x * t4.x + m4.y * t4.y) + (m4.z * t4.z + m4.w * t4.w);
;           }
;         }
;         float tt[16];
; #pragma unroll
;         for (int r = 0; r < 16; ++r) {
;           float s = acc[r];
; #pragma unroll
;           for (int q4 = 0; q4 < r; q4 += 4) {
;             const float4 m4 = *(const float4*)(sM + (r0 + r) * 68 + r0 + q4);
;             s += m4.x * tt[q4];
;             if (q4 + 1 < r) s += m4.y * tt[q4 + 1];
;             if (q4 + 2 < r) s += m4.z * tt[q4 + 2];
;             if (q4 + 3 < r) s += m4.w * tt[q4 + 3];
;           }
;           tt[r] = ((r0 + r == lane) ? 1.f : 0.f) - s;
;         }
; #pragma unroll
;         for (int r = 0; r < 16; r += 4) *(float4*)(mycol + r0 + r) = make_float4(tt[r], tt[r + 1], tt[r + 2], tt[r + 3]);
;       }
;     }
	v_fmac_f32_e32 v198, v238, v196
	v_fmac_f32_e32 v198, v239, v197
	v_cndmask_b32_e64 v178, 0, 1.0, vcc
	v_sub_f32_e32 v198, v178, v198
	ds_read_b128 v[238:241], v215 offset:14352
	v_cmp_eq_u32_e32 vcc, 51, v216
	s_waitcnt lgkmcnt(1)
	v_fmac_f32_e32 v199, v222, v196
	v_fmac_f32_e32 v199, v223, v197
	v_fmac_f32_e32 v199, v224, v198
	v_cndmask_b32_e64 v178, 0, 1.0, vcc
	v_sub_f32_e32 v199, v178, v199
	ds_read_b128 v[222:225], v215 offset:14624
	ds_read_b128 v[226:229], v215 offset:14640
	v_cmp_eq_u32_e32 vcc, 52, v216
	s_waitcnt lgkmcnt(2)
	v_fmac_f32_e32 v200, v238, v196
	v_fmac_f32_e32 v200, v239, v197
	v_fmac_f32_e32 v200, v240, v198
	v_fmac_f32_e32 v200, v241, v199
	v_cndmask_b32_e64 v178, 0, 1.0, vcc
	v_sub_f32_e32 v200, v178, v200
	ds_read_b128 v[238:241], v215 offset:14896
	ds_read_b128 v[242:245], v215 offset:14912
	v_cmp_eq_u32_e32 vcc, 53, v216
	s_waitcnt lgkmcnt(2)
	v_fmac_f32_e32 v201, v222, v196
	v_fmac_f32_e32 v201, v223, v197
	v_fmac_f32_e32 v201, v224, v198
	v_fmac_f32_e32 v201, v225, v199
	v_fmac_f32_e32 v201, v226, v200
	v_cndmask_b32_e64 v178, 0, 1.0, vcc
	v_sub_f32_e32 v201, v178, v201
	ds_read_b128 v[222:225], v215 offset:15168
	ds_read_b128 v[226:229], v215 offset:15184
	v_cmp_eq_u32_e32 vcc, 54, v216
	s_waitcnt lgkmcnt(2)
	v_fmac_f32_e32 v202, v238, v196
	v_fmac_f32_e32 v202, v239, v197
	v_fmac_f32_e32 v202, v240, v198
	v_fmac_f32_e32 v202, v241, v199
	v_fmac_f32_e32 v202, v242, v200
	v_fmac_f32_e32 v202, v243, v201
	v_cndmask_b32_e64 v178, 0, 1.0, vcc
	v_sub_f32_e32 v202, v178, v202
	ds_read_b128 v[238:241], v215 offset:15440
	ds_read_b128 v[242:245], v215 offset:15456
	v_cmp_eq_u32_e32 vcc, 55, v216
	s_waitcnt lgkmcnt(2)
	v_fmac_f32_e32 v203, v222, v196
	v_fmac_f32_e32 v203, v223, v197
	v_fmac_f32_e32 v203, v224, v198
	v_fmac_f32_e32 v203, v225, v199
	v_fmac_f32_e32 v203, v226, v200
	v_fmac_f32_e32 v203, v227, v201
	v_fmac_f32_e32 v203, v228, v202
	v_cndmask_b32_e64 v178, 0, 1.0, vcc
	v_sub_f32_e32 v203, v178, v203
	ds_read_b128 v[222:225], v215 offset:15712
	ds_read_b128 v[226:229], v215 offset:15728
	ds_read_b128 v[230:233], v215 offset:15744
	v_cmp_eq_u32_e32 vcc, 56, v216
	s_waitcnt lgkmcnt(3)
	v_fmac_f32_e32 v204, v238, v196
	v_fmac_f32_e32 v204, v239, v197
	v_fmac_f32_e32 v204, v240, v198
	v_fmac_f32_e32 v204, v241, v199
	v_fmac_f32_e32 v204, v242, v200
	v_fmac_f32_e32 v204, v243, v201
	v_fmac_f32_e32 v204, v244, v202
	v_fmac_f32_e32 v204, v245, v203
	v_cndmask_b32_e64 v178, 0, 1.0, vcc
	v_sub_f32_e32 v204, v178, v204
	ds_read_b128 v[238:241], v215 offset:15984
	ds_read_b128 v[242:245], v215 offset:16000
	ds_read_b128 v[248:251], v215 offset:16016
	v_cmp_eq_u32_e32 vcc, 57, v216
	s_waitcnt lgkmcnt(3)
	v_fmac_f32_e32 v205, v222, v196
	v_fmac_f32_e32 v205, v223, v197
	v_fmac_f32_e32 v205, v224, v198
	v_fmac_f32_e32 v205, v225, v199
	v_fmac_f32_e32 v205, v226, v200
	v_fmac_f32_e32 v205, v227, v201
	v_fmac_f32_e32 v205, v228, v202
	v_fmac_f32_e32 v205, v229, v203
	v_fmac_f32_e32 v205, v230, v204
	v_cndmask_b32_e64 v178, 0, 1.0, vcc
	v_sub_f32_e32 v205, v178, v205
	ds_read_b128 v[222:225], v215 offset:16256
	ds_read_b128 v[226:229], v215 offset:16272
	ds_read_b128 v[230:233], v215 offset:16288
	v_cmp_eq_u32_e32 vcc, 58, v216
	s_waitcnt lgkmcnt(3)
	v_fmac_f32_e32 v206, v238, v196
	v_fmac_f32_e32 v206, v239, v197
	v_fmac_f32_e32 v206, v240, v198
	v_fmac_f32_e32 v206, v241, v199
	v_fmac_f32_e32 v206, v242, v200
	v_fmac_f32_e32 v206, v243, v201
	v_fmac_f32_e32 v206, v244, v202
	v_fmac_f32_e32 v206, v245, v203
	v_fmac_f32_e32 v206, v248, v204
	v_fmac_f32_e32 v206, v249, v205
	v_cndmask_b32_e64 v178, 0, 1.0, vcc
	v_sub_f32_e32 v206, v178, v206
	ds_read_b128 v[238:241], v215 offset:16528
	ds_read_b128 v[242:245], v215 offset:16544
	ds_read_b128 v[248:251], v215 offset:16560
	v_cmp_eq_u32_e32 vcc, 59, v216
	s_waitcnt lgkmcnt(3)
; template <bool SIGNAL>
; __device__ __forceinline__ void phase2(const Params& p, unsigned char* smem, const int lo, const int hi, const int worker, const int nworkers) {
;     ...
;     float* sTc = (float*)sq;
;     if (wave == 0) {
;       float* mycol = sTc + lane * 68;
; #pragma unroll 1
;       for (int blk = 0; blk < 4; ++blk) {
;         const int r0 = blk * 16;
;         float acc[16];
; #pragma unroll
;         for (int r = 0; r < 16; ++r) acc[r] = 0.f;
; #pragma unroll 1
;         for (int j = 0; j < r0; j += 4) {
;           const float4 t4 = *(const float4*)(mycol + j);
; #pragma unroll
;           for (int r = 0; r < 16; ++r) {
;             const float4 m4 = *(const float4*)(sM + (r0 + r) * 68 + j);
;             acc[r] += (m4.x * t4.x + m4.y * t4.y) + (m4.z * t4.z + m4.w * t4.w);
;           }
;         }
;         float tt[16];
; #pragma unroll
;         for (int r = 0; r < 16; ++r) {
;           float s = acc[r];
; #pragma unroll
;           for (int q4 = 0; q4 < r; q4 += 4) {
;             const float4 m4 = *(const float4*)(sM + (r0 + r) * 68 + r0 + q4);
;             s += m4.x * tt[q4];
;             if (q4 + 1 < r) s += m4.y * tt[q4 + 1];
;             if (q4 + 2 < r) s += m4.z * tt[q4 + 2];
;             if (q4 + 3 < r) s += m4.w * tt[q4 + 3];
;           }
;           tt[r] = ((r0 + r == lane) ? 1.f : 0.f) - s;
;         }
; #pragma unroll
;         for (int r = 0; r < 16; r += 4) *(float4*)(mycol + r0 + r) = make_float4(tt[r], tt[r + 1], tt[r + 2], tt[r + 3]);
;       }
;     }
	v_fmac_f32_e32 v207, v222, v196
	v_fmac_f32_e32 v207, v223, v197
	v_fmac_f32_e32 v207, v224, v198
	v_fmac_f32_e32 v207, v225, v199
	v_fmac_f32_e32 v207, v226, v200
	v_fmac_f32_e32 v207, v227, v201
	v_fmac_f32_e32 v207, v228, v202
	v_fmac_f32_e32 v207, v229, v203
	v_fmac_f32_e32 v207, v230, v204
	v_fmac_f32_e32 v207, v231, v205
	v_fmac_f32_e32 v207, v232, v206
	v_cndmask_b32_e64 v178, 0, 1.0, vcc
	v_sub_f32_e32 v207, v178, v207
	ds_read_b128 v[222:225], v215 offset:16800
	ds_read_b128 v[226:229], v215 offset:16816
	ds_read_b128 v[230:233], v215 offset:16832
	ds_read_b128 v[234:237], v215 offset:16848
	v_cmp_eq_u32_e32 vcc, 60, v216
	s_waitcnt lgkmcnt(4)
	v_fmac_f32_e32 v208, v238, v196
	v_fmac_f32_e32 v208, v239, v197
	v_fmac_f32_e32 v208, v240, v198
	v_fmac_f32_e32 v208, v241, v199
	v_fmac_f32_e32 v208, v242, v200
	v_fmac_f32_e32 v208, v243, v201
	v_fmac_f32_e32 v208, v244, v202
	v_fmac_f32_e32 v208, v245, v203
	v_fmac_f32_e32 v208, v248, v204
	v_fmac_f32_e32 v208, v249, v205
	v_fmac_f32_e32 v208, v250, v206
	v_fmac_f32_e32 v208, v251, v207
	v_cndmask_b32_e64 v178, 0, 1.0, vcc
	v_sub_f32_e32 v208, v178, v208
	ds_read_b128 v[238:241], v215 offset:17072
	ds_read_b128 v[242:245], v215 offset:17088
	ds_read_b128 v[248:251], v215 offset:17104
	ds_read_b128 v[252:255], v215 offset:17120
	v_cmp_eq_u32_e32 vcc, 61, v216
	s_waitcnt lgkmcnt(4)
	v_fmac_f32_e32 v209, v222, v196
	v_fmac_f32_e32 v209, v223, v197
	v_fmac_f32_e32 v209, v224, v198
	v_fmac_f32_e32 v209, v225, v199
	v_fmac_f32_e32 v209, v226, v200
	v_fmac_f32_e32 v209, v227, v201
	v_fmac_f32_e32 v209, v228, v202
	v_fmac_f32_e32 v209, v229, v203
	v_fmac_f32_e32 v209, v230, v204
	v_fmac_f32_e32 v209, v231, v205
	v_fmac_f32_e32 v209, v232, v206
	v_fmac_f32_e32 v209, v233, v207
	v_fmac_f32_e32 v209, v234, v208
	v_cndmask_b32_e64 v178, 0, 1.0, vcc
	v_sub_f32_e32 v209, v178, v209
	ds_read_b128 v[222:225], v215 offset:17344
	ds_read_b128 v[226:229], v215 offset:17360
	ds_read_b128 v[230:233], v215 offset:17376
	ds_read_b128 v[234:237], v215 offset:17392
	v_cmp_eq_u32_e32 vcc, 62, v216
	s_waitcnt lgkmcnt(4)
	v_fmac_f32_e32 v210, v238, v196
	v_fmac_f32_e32 v210, v239, v197
	v_fmac_f32_e32 v210, v240, v198
	v_fmac_f32_e32 v210, v241, v199
	v_fmac_f32_e32 v210, v242, v200
	v_fmac_f32_e32 v210, v243, v201
	v_fmac_f32_e32 v210, v244, v202
	v_fmac_f32_e32 v210, v245, v203
	v_fmac_f32_e32 v210, v248, v204
	v_fmac_f32_e32 v210, v249, v205
	v_fmac_f32_e32 v210, v250, v206
	v_fmac_f32_e32 v210, v251, v207
	v_fmac_f32_e32 v210, v252, v208
	v_fmac_f32_e32 v210, v253, v209
	v_cndmask_b32_e64 v178, 0, 1.0, vcc
	v_sub_f32_e32 v210, v178, v210
	v_cmp_eq_u32_e32 vcc, 63, v216
	s_waitcnt lgkmcnt(0)
	v_fmac_f32_e32 v211, v222, v196
	v_fmac_f32_e32 v211, v223, v197
	v_fmac_f32_e32 v211, v224, v198
	v_fmac_f32_e32 v211, v225, v199
	v_fmac_f32_e32 v211, v226, v200
	v_fmac_f32_e32 v211, v227, v201
	v_fmac_f32_e32 v211, v228, v202
	v_fmac_f32_e32 v211, v229, v203
	v_fmac_f32_e32 v211, v230, v204
	v_fmac_f32_e32 v211, v231, v205
	v_fmac_f32_e32 v211, v232, v206
	v_fmac_f32_e32 v211, v233, v207
	v_fmac_f32_e32 v211, v234, v208
	v_fmac_f32_e32 v211, v235, v209
	v_fmac_f32_e32 v211, v236, v210
	v_cndmask_b32_e64 v178, 0, 1.0, vcc
	v_sub_f32_e32 v211, v178, v211
	ds_write_b128 v212, v[196:199] offset:192
	ds_write_b128 v212, v[200:203] offset:208
	ds_write_b128 v212, v[204:207] offset:224
	ds_write_b128 v212, v[208:211] offset:240
	s_waitcnt lgkmcnt(0)
